# Up epilogue: waves that skip the tile-top side stores sleep 4x64 cycles at that point so both waves of a SIMD stay in phase through the rest of the epilogue
# baseline (speedup 1.0000x reference)
;     __device__ __forceinline__ void operator()(const f32x4 (&acc)[2][2][4][2], const pg8::Unit& u, int ui, int wr, int wc, int fr, int fq) const {
;     ...
;             for (int m = 0; m < 4; ++m) {
;                 const int rl = ai * 128 + wr * 64 + m * 16 + fr;
;                 f32x4 a[2], o[2];
; #pragma unroll
;                 for (int n = 0; n < 2; ++n) {
;                     a[n] = acc[ai][0][m][n] * rr[ai][m];
;                     const f32x4 v = acc[ai][1][m][n] * rr[ai][m];
; #pragma unroll
;                     for (int q = 0; q < 2; ++q) {
;                         const int xb = __builtin_bit_cast(int, __builtin_amdgcn_cvt_pkrtz(a[n][2 * q], a[n][2 * q + 1]));
;                         const int t1 = __builtin_amdgcn_mov_dpp(xb, 0x121, 0xf, 0xf, true), t2 = __builtin_amdgcn_mov_dpp(xb, 0x122, 0xf, 0xf, true);
;                         const h2 p1 = __builtin_bit_cast(h2, (fr == 0) ? t1p[n][q] : t1), p2 = __builtin_bit_cast(h2, (fr < 2) ? t2p[n][q] : t2), x2 = __builtin_bit_cast(h2, xb);
;                         t1p[n][q] = t1; t2p[n][q] = t2;
;                         const h2 c = p2 * w0h[n][q] + (p1 * w1h[n][q] + (x2 * w2h[n][q] + bbh[n][q]));
;                         const h2 ea = c * (h2){(_Float16)(-LOG2E), (_Float16)(-LOG2E)};
;                         h2 ex; ex.x = __builtin_exp2f16(ea.x); ex.y = __builtin_exp2f16(ea.y);
;                         const h2 dn = ex + (h2){(_Float16)1.f, (_Float16)1.f};
;                         h2 rc; rc.x = __builtin_amdgcn_rcph(dn.x); rc.y = __builtin_amdgcn_rcph(dn.y);
;                         const h2 sg = c * rc;
;                         o[n][2 * q] = (float)sg.x * v[2 * q]; o[n][2 * q + 1] = (float)sg.y * v[2 * q + 1];
;                     }
;                 }
;                 u32x4 pk; pk.x = cvt_pk_bf16(o[0][0], o[0][1]); pk.y = cvt_pk_bf16(o[0][2], o[0][3]); pk.z = cvt_pk_bf16(o[1][0], o[1][1]); pk.w = cvt_pk_bf16(o[1][2], o[1][3]);
;                 *(u32x4*)(U + (size_t)(u.pm * 256 + rl) * FF + fcol) = pk;
;                 if (ai == 0 && m == 0 && wr == 0 && fr < 2) {
; #pragma unroll
;                     for (int n = 0; n < 2; ++n) { *(f32x4*)(topa + (size_t)(u.pm * 2 + fr) * FF + fcol + 4 * n) = a[n]; *(f32x4*)(topv + (size_t)(u.pm * 2 + fr) * FF + fcol + 4 * n) = acc[0][1][0][n] * rr[0][0]; }
;                 }
.LBB0_239:
	v_cvt_pk_f16_f32 v225, v146, v147
	v_cvt_pk_f16_f32 v146, v130, v131
	v_cvt_pk_f16_f32 v131, v136, v137
	s_waitcnt lgkmcnt(1)
	v_cvt_pkrtz_f16_f32 v136, v162, v163
	v_cvt_pk_f16_f32 v134, v134, v135
	v_cvt_pk_f16_f32 v135, v138, v139
	v_cvt_pk_f16_f32 v130, v132, v133
	v_cvt_pk_f16_f32 v132, v140, v141
	v_mov_b32_dpp v139, v136 row_ror:1 row_mask:0xf bank_mask:0xf bound_ctrl:1
	v_mov_b32_dpp v140, v136 row_ror:2 row_mask:0xf bank_mask:0xf bound_ctrl:1
	v_cvt_pkrtz_f16_f32 v136, v164, v165
	v_pk_mul_f32 v[126:127], v[126:127], v[204:205] op_sel_hi:[1,0]
	v_cvt_pk_f16_f32 v147, v148, v149
	v_cvt_pk_f16_f32 v148, v152, v153
	v_cvt_pk_f16_f32 v138, v142, v143
	v_mov_b32_dpp v141, v136 row_ror:1 row_mask:0xf bank_mask:0xf bound_ctrl:1
	v_mov_b32_dpp v142, v136 row_ror:2 row_mask:0xf bank_mask:0xf bound_ctrl:1
	s_waitcnt lgkmcnt(0)
	v_cvt_pkrtz_f16_f32 v136, v166, v167
	v_cvt_pkrtz_f16_f32 v152, v126, v127
	v_cvt_pk_f16_f32 v154, v154, v155
	v_cvt_pk_f16_f32 v155, v158, v159
	v_cvt_pk_f16_f32 v133, v144, v145
	v_mov_b32_dpp v143, v136 row_ror:1 row_mask:0xf bank_mask:0xf bound_ctrl:1
	v_mov_b32_dpp v144, v136 row_ror:2 row_mask:0xf bank_mask:0xf bound_ctrl:1
	v_mov_b32_dpp v136, v152 row_ror:1 row_mask:0xf bank_mask:0xf bound_ctrl:1
	v_cvt_pk_f16_f32 v151, v150, v151
	v_mov_b32_dpp v137, v152 row_ror:2 row_mask:0xf bank_mask:0xf bound_ctrl:1
	v_cndmask_b32_e64 v139, v136, v139, s[68:69]
	v_pk_fma_f16 v152, v154, v152, v155
	v_cndmask_b32_e64 v140, v137, v140, s[76:77]
	v_pk_fma_f16 v139, v151, v139, v152
	v_pk_mul_f32 v[128:129], v[128:129], v[204:205] op_sel_hi:[1,0]
	v_pk_fma_f16 v152, v225, v140, v139
	v_cvt_pk_f16_f32 v149, v156, v157
	v_pk_mul_f16 v139, v152, s52 op_sel_hi:[1,0]
	v_cvt_pkrtz_f16_f32 v157, v128, v129
	v_exp_f16_sdwa v139, v139 dst_sel:WORD_1 dst_unused:UNUSED_PRESERVE src0_sel:WORD_1
	s_nop 0
	v_exp_f16_sdwa v139, v139 dst_sel:WORD_0 dst_unused:UNUSED_PRESERVE src0_sel:WORD_0
	v_cvt_pk_f16_f32 v150, v160, v161
	v_pk_mul_f32 v[118:119], v[118:119], v[204:205] op_sel_hi:[1,0]
	v_pk_mul_f32 v[120:121], v[120:121], v[204:205] op_sel_hi:[1,0]
	v_pk_add_f16 v139, v139, 1.0 op_sel_hi:[1,0]
	v_mov_b32_dpp v140, v157 row_ror:2 row_mask:0xf bank_mask:0xf bound_ctrl:1
	v_rcp_f16_e32 v153, v139
	s_nop 0
	v_rcp_f16_sdwa v153, v139 dst_sel:WORD_1 dst_unused:UNUSED_PRESERVE src0_sel:WORD_1
	v_mov_b32_dpp v139, v157 row_ror:1 row_mask:0xf bank_mask:0xf bound_ctrl:1
	v_cndmask_b32_e64 v141, v139, v141, s[68:69]
	v_pk_fma_f16 v157, v149, v157, v150
	v_cndmask_b32_e64 v142, v140, v142, s[76:77]
	v_pk_fma_f16 v141, v148, v141, v157
	v_pk_fma_f16 v141, v147, v142, v141
	v_cvt_pkrtz_f16_f32 v145, v168, v169
	v_pk_mul_f16 v142, v141, s52 op_sel_hi:[1,0]
	v_cvt_pkrtz_f16_f32 v159, v120, v121
	v_exp_f16_sdwa v142, v142 dst_sel:WORD_1 dst_unused:UNUSED_PRESERVE src0_sel:WORD_1
	s_nop 0
	v_exp_f16_sdwa v142, v142 dst_sel:WORD_0 dst_unused:UNUSED_PRESERVE src0_sel:WORD_0
	v_mov_b32_dpp v158, v145 row_ror:1 row_mask:0xf bank_mask:0xf bound_ctrl:1
	v_mov_b32_dpp v145, v145 row_ror:2 row_mask:0xf bank_mask:0xf bound_ctrl:1
	v_pk_mul_f32 v[124:125], v[124:125], v[204:205] op_sel_hi:[1,0]
	v_pk_add_f16 v142, v142, 1.0 op_sel_hi:[1,0]
	v_pk_mul_f16 v153, v152, v153
	v_rcp_f16_sdwa v142, v142 dst_sel:WORD_1 dst_unused:UNUSED_PRESERVE src0_sel:WORD_1
	s_nop 0
	v_rcp_f16_sdwa v142, v142 dst_sel:WORD_0 dst_unused:UNUSED_PRESERVE src0_sel:WORD_0
	v_pk_mul_f32 v[122:123], v[122:123], v[204:205] op_sel_hi:[1,0]
	v_cvt_pkrtz_f16_f32 v156, v118, v119
	v_pk_mul_f16 v157, v141, v142
	v_fma_mix_f32 v152, v153, v122, 0 op_sel_hi:[1,0,0]
	v_fma_mix_f32 v153, v153, v123, 0 op_sel:[1,0,0] op_sel_hi:[1,0,0]
	v_mov_b32_dpp v141, v156 row_ror:1 row_mask:0xf bank_mask:0xf bound_ctrl:1
	v_mov_b32_dpp v142, v156 row_ror:2 row_mask:0xf bank_mask:0xf bound_ctrl:1
	v_cndmask_b32_e64 v143, v141, v143, s[68:69]
	v_pk_fma_f16 v156, v135, v156, v138
	v_cndmask_b32_e64 v144, v142, v144, s[76:77]
	v_pk_fma_f16 v143, v134, v143, v156
	v_pk_fma_f16 v160, v146, v144, v143
	v_pk_mul_f16 v143, v160, s52 op_sel_hi:[1,0]
	v_pk_mul_f32 v[114:115], v[114:115], v[204:205] op_sel_hi:[1,0]
	v_exp_f16_sdwa v143, v143 dst_sel:WORD_1 dst_unused:UNUSED_PRESERVE src0_sel:WORD_1
	s_nop 0
	v_exp_f16_sdwa v143, v143 dst_sel:WORD_0 dst_unused:UNUSED_PRESERVE src0_sel:WORD_0
	v_lshl_add_u32 v224, s40, 8, v206
	v_pk_mul_f32 v[116:117], v[116:117], v[204:205] op_sel_hi:[1,0]
	v_lshl_add_u32 v223, s40, 1, v1
	v_pk_add_f16 v143, v143, 1.0 op_sel_hi:[1,0]
	v_mov_b32_dpp v144, v159 row_ror:2 row_mask:0xf bank_mask:0xf bound_ctrl:1
	v_rcp_f16_e32 v161, v143
	v_rcp_f16_sdwa v162, v143 dst_sel:DWORD dst_unused:UNUSED_PAD src0_sel:WORD_1
	v_mov_b32_dpp v143, v159 row_ror:1 row_mask:0xf bank_mask:0xf bound_ctrl:1
	v_cndmask_b32_e64 v158, v143, v158, s[68:69]
	v_pk_fma_f16 v159, v132, v159, v133
	v_cndmask_b32_e64 v145, v144, v145, s[76:77]
	v_pk_fma_f16 v158, v131, v158, v159
	s_nop 0
	v_pk_fma_f16 v145, v130, v145, v158
	s_nop 0
	v_pk_mul_f16 v158, v145, s52 op_sel_hi:[1,0]
	s_nop 0
	v_exp_f16_e32 v163, v158
	v_exp_f16_sdwa v164, v158 dst_sel:DWORD dst_unused:UNUSED_PAD src0_sel:WORD_1
	v_fma_mix_f32 v158, v157, v124, 0 op_sel_hi:[1,0,0]
	v_fma_mix_f32 v159, v157, v125, 0 op_sel:[1,0,0] op_sel_hi:[1,0,0]
	v_pack_b32_f16 v156, v161, v162
	v_pack_b32_f16 v157, v163, v164
	v_pk_add_f16 v157, v157, 1.0 op_sel_hi:[1,0]
	s_nop 0
	v_rcp_f16_e32 v161, v157
	v_rcp_f16_sdwa v162, v157 dst_sel:DWORD dst_unused:UNUSED_PAD src0_sel:WORD_1
	v_pk_mul_f16 v157, v160, v156
	v_pack_b32_f16 v160, v161, v162
	v_pk_mul_f16 v145, v145, v160
	v_fma_mix_f32 v162, v157, v114, 0 op_sel_hi:[1,0,0]
	v_fma_mix_f32 v163, v157, v115, 0 op_sel:[1,0,0] op_sel_hi:[1,0,0]
	v_cvt_pk_bf16_f32 v156, v152, v153
	v_mov_b64_e32 v[152:153], s[50:51]
	v_mad_i64_i32 v[152:153], s[20:21], v224, s38, v[152:153]
	v_fma_mix_f32 v160, v145, v116, 0 op_sel_hi:[1,0,0]
	v_fma_mix_f32 v161, v145, v117, 0 op_sel:[1,0,0] op_sel_hi:[1,0,0]
	v_cvt_pk_bf16_f32 v157, v158, v159
	v_cvt_pk_bf16_f32 v158, v162, v163
	v_cvt_pk_bf16_f32 v159, v160, v161
	v_lshl_add_u64 v[152:153], v[194:195], 1, v[152:153]
	global_store_dwordx4 v[152:153], v[156:159], off
	s_and_saveexec_b64 s[20:21], s[18:19]
	s_cbranch_execz .Lup_top_skip
	s_movk_i32 s12, 0x2c00
	v_mov_b64_e32 v[156:157], s[58:59]
	v_mov_b64_e32 v[152:153], s[94:95]
	v_mad_i64_i32 v[156:157], s[18:19], v223, s12, v[156:157]
	v_mad_i64_i32 v[152:153], s[18:19], v223, s12, v[152:153]
	v_lshl_add_u64 v[156:157], v[156:157], 0, v[202:203]
	v_lshl_add_u64 v[152:153], v[152:153], 0, v[202:203]
	global_store_dwordx4 v[156:157], v[126:129], off
	global_store_dwordx4 v[152:153], v[122:125], off
	global_store_dwordx4 v[156:157], v[118:121], off offset:16
	global_store_dwordx4 v[152:153], v[114:117], off offset:16
	s_branch .LBB0_241
.Lup_top_skip:
	s_sleep 4
